# k30: GEMM epilogue result stores use the SGPR base + one 32-bit v_lshl_add_u32 offset (saddr) instead of ashr + 64-bit shift + two 64-bit VALU adds per row group (56 groups)
# baseline (speedup 1.0000x reference)
.LBB0_138:
	s_lshl_b32 s0, s26, 8
	v_add_u32_e32 v144, s0, v146
	v_ashrrev_i32_e32 v145, 31, v144
	v_lshl_or_b32 v160, s52, 8, v155
	v_lshlrev_b64 v[144:145], 11, v[144:145]
	v_ashrrev_i32_e32 v161, 31, v160
	v_lshl_add_u64 v[162:163], s[82:83], 0, v[144:145]
	v_lshlrev_b64 v[144:145], 1, v[160:161]
	v_lshl_add_u64 v[160:161], v[162:163], 0, v[144:145]
	v_cvt_pk_bf16_f32 v124, v124, v125
	v_cvt_pk_bf16_f32 v125, v126, v127
	v_cvt_pk_bf16_f32 v126, v120, v121
	v_cvt_pk_bf16_f32 v127, v122, v123
	global_store_dwordx4 v[160:161], v[124:127], off
	v_cvt_pk_bf16_f32 v112, v112, v113
	v_cvt_pk_bf16_f32 v113, v114, v115
	v_cvt_pk_bf16_f32 v114, v104, v105
	v_add_u32_e32 v104, s0, v148
	v_cvt_pk_bf16_f32 v115, v106, v107
	global_store_dwordx4 v[160:161], v[112:115], off offset:256
	s_andn2_b64 vcc, exec, s[4:5]
	s_nop 0
	v_lshl_add_u32 v112, v104, 11, v144
	v_cvt_pk_bf16_f32 v104, v116, v117
	v_cvt_pk_bf16_f32 v105, v118, v119
	v_cvt_pk_bf16_f32 v106, v108, v109
	v_cvt_pk_bf16_f32 v107, v110, v111
	global_store_dwordx4 v112, v[104:107], s[82:83]
	v_cvt_pk_bf16_f32 v96, v96, v97
	v_cvt_pk_bf16_f32 v97, v98, v99
	v_cvt_pk_bf16_f32 v98, v88, v89
	v_add_u32_e32 v88, s0, v149
	v_cvt_pk_bf16_f32 v99, v90, v91
	global_store_dwordx4 v112, v[96:99], s[82:83] offset:256
	s_nop 1
	v_lshl_add_u32 v96, v88, 11, v144
	v_cvt_pk_bf16_f32 v88, v100, v101
	v_cvt_pk_bf16_f32 v89, v102, v103
	v_cvt_pk_bf16_f32 v90, v92, v93
	v_cvt_pk_bf16_f32 v91, v94, v95
	global_store_dwordx4 v96, v[88:91], s[82:83]
	v_cvt_pk_bf16_f32 v80, v80, v81
	v_cvt_pk_bf16_f32 v81, v82, v83
	v_cvt_pk_bf16_f32 v82, v72, v73
	v_add_u32_e32 v72, s0, v150
	v_cvt_pk_bf16_f32 v83, v74, v75
	global_store_dwordx4 v96, v[80:83], s[82:83] offset:256
	s_nop 1
	v_lshl_add_u32 v80, v72, 11, v144
	v_cvt_pk_bf16_f32 v72, v84, v85
	v_cvt_pk_bf16_f32 v73, v86, v87
	v_cvt_pk_bf16_f32 v74, v76, v77
	v_cvt_pk_bf16_f32 v75, v78, v79
	global_store_dwordx4 v80, v[72:75], s[82:83]
	v_cvt_pk_bf16_f32 v68, v68, v69
	v_cvt_pk_bf16_f32 v69, v70, v71
	v_cvt_pk_bf16_f32 v70, v64, v65
	v_add_u32_e32 v64, s0, v151
	v_lshl_add_u32 v64, v64, 11, v144
	v_cvt_pk_bf16_f32 v71, v66, v67
	global_store_dwordx4 v80, v[68:71], s[82:83] offset:256
	v_cvt_pk_bf16_f32 v60, v60, v61
	v_cvt_pk_bf16_f32 v61, v62, v63
	v_cvt_pk_bf16_f32 v62, v56, v57
	v_cvt_pk_bf16_f32 v63, v58, v59
	global_store_dwordx4 v64, v[60:63], s[82:83]
	v_cvt_pk_bf16_f32 v48, v48, v49
	v_cvt_pk_bf16_f32 v49, v50, v51
	v_cvt_pk_bf16_f32 v50, v40, v41
	v_add_u32_e32 v40, s0, v152
	v_cvt_pk_bf16_f32 v51, v42, v43
	global_store_dwordx4 v64, v[48:51], s[82:83] offset:256
	s_nop 1
	v_lshl_add_u32 v48, v40, 11, v144
	v_cvt_pk_bf16_f32 v40, v52, v53
	v_cvt_pk_bf16_f32 v41, v54, v55
	v_cvt_pk_bf16_f32 v42, v44, v45
	v_cvt_pk_bf16_f32 v43, v46, v47
	global_store_dwordx4 v48, v[40:43], s[82:83]
	v_cvt_pk_bf16_f32 v32, v32, v33
	v_cvt_pk_bf16_f32 v33, v34, v35
	v_cvt_pk_bf16_f32 v34, v24, v25
	v_add_u32_e32 v24, s0, v153
	v_cvt_pk_bf16_f32 v35, v26, v27
	global_store_dwordx4 v48, v[32:35], s[82:83] offset:256
	s_nop 1
	v_lshl_add_u32 v32, v24, 11, v144
	v_cvt_pk_bf16_f32 v24, v36, v37
	v_cvt_pk_bf16_f32 v25, v38, v39
	v_cvt_pk_bf16_f32 v26, v28, v29
	v_cvt_pk_bf16_f32 v27, v30, v31
	global_store_dwordx4 v32, v[24:27], s[82:83]
	v_cvt_pk_bf16_f32 v16, v16, v17
	v_cvt_pk_bf16_f32 v17, v18, v19
	v_cvt_pk_bf16_f32 v18, v8, v9
	v_add_u32_e32 v8, s0, v154
	v_cvt_pk_bf16_f32 v19, v10, v11
	global_store_dwordx4 v32, v[16:19], s[82:83] offset:256
	s_mov_b64 s[0:1], -1
	s_nop 0
	v_lshl_add_u32 v16, v8, 11, v144
	v_cvt_pk_bf16_f32 v8, v20, v21
	v_cvt_pk_bf16_f32 v9, v22, v23
	v_cvt_pk_bf16_f32 v10, v12, v13
	v_cvt_pk_bf16_f32 v11, v14, v15
	global_store_dwordx4 v16, v[8:11], s[82:83]
	v_cvt_pk_bf16_f32 v4, v4, v5
	v_cvt_pk_bf16_f32 v5, v6, v7
	v_cvt_pk_bf16_f32 v6, v0, v1
	v_cvt_pk_bf16_f32 v7, v2, v3
	global_store_dwordx4 v16, v[4:7], s[82:83] offset:256
	s_cbranch_vccnz .LBB0_127
	s_andn2_b64 vcc, exec, s[10:11]
	s_cbranch_vccnz .LBB0_126
	s_barrier
	s_branch .LBB0_126

.LBB0_158:
	s_lshl_b32 s0, s24, 8
	v_add_u32_e32 v144, s0, v146
	v_ashrrev_i32_e32 v145, 31, v144
	v_lshl_or_b32 v160, s42, 8, v155
	v_readlane_b32 s44, v254, 0
	v_lshlrev_b64 v[144:145], 11, v[144:145]
	v_readlane_b32 s50, v254, 6
	v_readlane_b32 s51, v254, 7
	v_ashrrev_i32_e32 v161, 31, v160
	v_cvt_pk_bf16_f32 v124, v124, v125
	v_cvt_pk_bf16_f32 v125, v126, v127
	v_cvt_pk_bf16_f32 v126, v120, v121
	v_cvt_pk_bf16_f32 v127, v122, v123
	s_nop 0
	v_lshl_add_u64 v[162:163], s[50:51], 0, v[144:145]
	v_lshlrev_b64 v[144:145], 1, v[160:161]
	v_lshl_add_u64 v[160:161], v[162:163], 0, v[144:145]
	global_store_dwordx4 v[160:161], v[124:127], off
	v_cvt_pk_bf16_f32 v112, v112, v113
	v_cvt_pk_bf16_f32 v113, v114, v115
	v_cvt_pk_bf16_f32 v114, v104, v105
	v_add_u32_e32 v104, s0, v148
	v_cvt_pk_bf16_f32 v115, v106, v107
	global_store_dwordx4 v[160:161], v[112:115], off offset:256
	s_andn2_b64 vcc, exec, s[6:7]
	v_readlane_b32 s45, v254, 1
	v_lshl_add_u32 v112, v104, 11, v144
	v_cvt_pk_bf16_f32 v104, v116, v117
	v_cvt_pk_bf16_f32 v105, v118, v119
	v_cvt_pk_bf16_f32 v106, v108, v109
	v_cvt_pk_bf16_f32 v107, v110, v111
	global_store_dwordx4 v112, v[104:107], s[50:51]
	v_cvt_pk_bf16_f32 v96, v96, v97
	v_cvt_pk_bf16_f32 v97, v98, v99
	v_cvt_pk_bf16_f32 v98, v88, v89
	v_add_u32_e32 v88, s0, v149
	v_cvt_pk_bf16_f32 v99, v90, v91
	global_store_dwordx4 v112, v[96:99], s[50:51] offset:256
	v_readlane_b32 s46, v254, 2
	v_readlane_b32 s47, v254, 3
	v_lshl_add_u32 v96, v88, 11, v144
	v_cvt_pk_bf16_f32 v88, v100, v101
	v_cvt_pk_bf16_f32 v89, v102, v103
	v_cvt_pk_bf16_f32 v90, v92, v93
	v_cvt_pk_bf16_f32 v91, v94, v95
	global_store_dwordx4 v96, v[88:91], s[50:51]
	v_cvt_pk_bf16_f32 v80, v80, v81
	v_cvt_pk_bf16_f32 v81, v82, v83
	v_cvt_pk_bf16_f32 v82, v72, v73
	v_add_u32_e32 v72, s0, v150
	v_cvt_pk_bf16_f32 v83, v74, v75
	global_store_dwordx4 v96, v[80:83], s[50:51] offset:256
	v_readlane_b32 s48, v254, 4
	v_readlane_b32 s49, v254, 5
	v_lshl_add_u32 v80, v72, 11, v144
	v_cvt_pk_bf16_f32 v72, v84, v85
	v_cvt_pk_bf16_f32 v73, v86, v87
	v_cvt_pk_bf16_f32 v74, v76, v77
	v_cvt_pk_bf16_f32 v75, v78, v79
	global_store_dwordx4 v80, v[72:75], s[50:51]
	v_cvt_pk_bf16_f32 v68, v68, v69
	v_cvt_pk_bf16_f32 v69, v70, v71
	v_cvt_pk_bf16_f32 v70, v64, v65
	v_add_u32_e32 v64, s0, v151
	v_lshl_add_u32 v64, v64, 11, v144
	v_cvt_pk_bf16_f32 v71, v66, v67
	global_store_dwordx4 v80, v[68:71], s[50:51] offset:256
	v_cvt_pk_bf16_f32 v60, v60, v61
	v_cvt_pk_bf16_f32 v61, v62, v63
	v_cvt_pk_bf16_f32 v62, v56, v57
	v_cvt_pk_bf16_f32 v63, v58, v59
	global_store_dwordx4 v64, v[60:63], s[50:51]
	v_cvt_pk_bf16_f32 v48, v48, v49
	v_cvt_pk_bf16_f32 v49, v50, v51
	v_cvt_pk_bf16_f32 v50, v40, v41
	v_add_u32_e32 v40, s0, v152
	v_cvt_pk_bf16_f32 v51, v42, v43
	global_store_dwordx4 v64, v[48:51], s[50:51] offset:256
	s_nop 1
	v_lshl_add_u32 v48, v40, 11, v144
	v_cvt_pk_bf16_f32 v40, v52, v53
	v_cvt_pk_bf16_f32 v41, v54, v55
	v_cvt_pk_bf16_f32 v42, v44, v45
	v_cvt_pk_bf16_f32 v43, v46, v47
	global_store_dwordx4 v48, v[40:43], s[50:51]
	v_cvt_pk_bf16_f32 v32, v32, v33
	v_cvt_pk_bf16_f32 v33, v34, v35
	v_cvt_pk_bf16_f32 v34, v24, v25
	v_add_u32_e32 v24, s0, v153
	v_cvt_pk_bf16_f32 v35, v26, v27
	global_store_dwordx4 v48, v[32:35], s[50:51] offset:256
	s_nop 1
	v_lshl_add_u32 v32, v24, 11, v144
	v_cvt_pk_bf16_f32 v24, v36, v37
	v_cvt_pk_bf16_f32 v25, v38, v39
	v_cvt_pk_bf16_f32 v26, v28, v29
	v_cvt_pk_bf16_f32 v27, v30, v31
	global_store_dwordx4 v32, v[24:27], s[50:51]
	v_cvt_pk_bf16_f32 v20, v20, v21
	v_cvt_pk_bf16_f32 v21, v22, v23
	v_cvt_pk_bf16_f32 v22, v12, v13
	v_add_u32_e32 v12, s0, v154
	v_cvt_pk_bf16_f32 v23, v14, v15
	global_store_dwordx4 v32, v[20:23], s[50:51] offset:256
	s_mov_b64 s[0:1], -1
	s_nop 0
	v_lshl_add_u32 v20, v12, 11, v144
	v_cvt_pk_bf16_f32 v12, v16, v17
	v_cvt_pk_bf16_f32 v13, v18, v19
	v_cvt_pk_bf16_f32 v14, v8, v9
	v_cvt_pk_bf16_f32 v15, v10, v11
	global_store_dwordx4 v20, v[12:15], s[50:51]
	v_cvt_pk_bf16_f32 v4, v4, v5
	v_cvt_pk_bf16_f32 v5, v6, v7
	v_cvt_pk_bf16_f32 v6, v0, v1
	v_cvt_pk_bf16_f32 v7, v2, v3
	global_store_dwordx4 v20, v[4:7], s[50:51] offset:256
	s_cbranch_vccnz .LBB0_147
	s_andn2_b64 vcc, exec, s[10:11]
	s_cbranch_vccnz .LBB0_146
	s_barrier
	s_branch .LBB0_146

.LBB0_178:
	s_lshl_b32 s0, s26, 8
	v_add_u32_e32 v144, s0, v146
	v_ashrrev_i32_e32 v145, 31, v144
	v_lshl_or_b32 v160, s58, 8, v155
	v_lshlrev_b64 v[144:145], 11, v[144:145]
	v_ashrrev_i32_e32 v161, 31, v160
	v_lshl_add_u64 v[162:163], s[14:15], 0, v[144:145]
	v_lshlrev_b64 v[144:145], 1, v[160:161]
	v_lshl_add_u64 v[160:161], v[162:163], 0, v[144:145]
	v_cvt_pk_bf16_f32 v124, v124, v125
	v_cvt_pk_bf16_f32 v125, v126, v127
	v_cvt_pk_bf16_f32 v126, v120, v121
	v_cvt_pk_bf16_f32 v127, v122, v123
	global_store_dwordx4 v[160:161], v[124:127], off
	v_cvt_pk_bf16_f32 v112, v112, v113
	v_cvt_pk_bf16_f32 v113, v114, v115
	v_cvt_pk_bf16_f32 v114, v104, v105
	v_add_u32_e32 v104, s0, v148
	v_cvt_pk_bf16_f32 v115, v106, v107
	global_store_dwordx4 v[160:161], v[112:115], off offset:256
	s_andn2_b64 vcc, exec, s[6:7]
	s_nop 0
	v_lshl_add_u32 v112, v104, 11, v144
	v_cvt_pk_bf16_f32 v104, v116, v117
	v_cvt_pk_bf16_f32 v105, v118, v119
	v_cvt_pk_bf16_f32 v106, v108, v109
	v_cvt_pk_bf16_f32 v107, v110, v111
	global_store_dwordx4 v112, v[104:107], s[14:15]
	v_cvt_pk_bf16_f32 v96, v96, v97
	v_cvt_pk_bf16_f32 v97, v98, v99
	v_cvt_pk_bf16_f32 v98, v88, v89
	v_add_u32_e32 v88, s0, v149
	v_cvt_pk_bf16_f32 v99, v90, v91
	global_store_dwordx4 v112, v[96:99], s[14:15] offset:256
	s_nop 1
	v_lshl_add_u32 v96, v88, 11, v144
	v_cvt_pk_bf16_f32 v88, v100, v101
	v_cvt_pk_bf16_f32 v89, v102, v103
	v_cvt_pk_bf16_f32 v90, v92, v93
	v_cvt_pk_bf16_f32 v91, v94, v95
	global_store_dwordx4 v96, v[88:91], s[14:15]
	v_cvt_pk_bf16_f32 v80, v80, v81
	v_cvt_pk_bf16_f32 v81, v82, v83
	v_cvt_pk_bf16_f32 v82, v72, v73
	v_add_u32_e32 v72, s0, v150
	v_cvt_pk_bf16_f32 v83, v74, v75
	global_store_dwordx4 v96, v[80:83], s[14:15] offset:256
	s_nop 1
	v_lshl_add_u32 v80, v72, 11, v144
	v_cvt_pk_bf16_f32 v72, v84, v85
	v_cvt_pk_bf16_f32 v73, v86, v87
	v_cvt_pk_bf16_f32 v74, v76, v77
	v_cvt_pk_bf16_f32 v75, v78, v79
	global_store_dwordx4 v80, v[72:75], s[14:15]
	v_cvt_pk_bf16_f32 v68, v68, v69
	v_cvt_pk_bf16_f32 v69, v70, v71
	v_cvt_pk_bf16_f32 v70, v64, v65
	v_add_u32_e32 v64, s0, v151
	v_lshl_add_u32 v64, v64, 11, v144
	v_cvt_pk_bf16_f32 v71, v66, v67
	global_store_dwordx4 v80, v[68:71], s[14:15] offset:256
	v_cvt_pk_bf16_f32 v60, v60, v61
	v_cvt_pk_bf16_f32 v61, v62, v63
	v_cvt_pk_bf16_f32 v62, v56, v57
	v_cvt_pk_bf16_f32 v63, v58, v59
	global_store_dwordx4 v64, v[60:63], s[14:15]
	v_cvt_pk_bf16_f32 v48, v48, v49
	v_cvt_pk_bf16_f32 v49, v50, v51
	v_cvt_pk_bf16_f32 v50, v40, v41
	v_add_u32_e32 v40, s0, v152
	v_cvt_pk_bf16_f32 v51, v42, v43
	global_store_dwordx4 v64, v[48:51], s[14:15] offset:256
	s_nop 1
	v_lshl_add_u32 v48, v40, 11, v144
	v_cvt_pk_bf16_f32 v40, v52, v53
	v_cvt_pk_bf16_f32 v41, v54, v55
	v_cvt_pk_bf16_f32 v42, v44, v45
	v_cvt_pk_bf16_f32 v43, v46, v47
	global_store_dwordx4 v48, v[40:43], s[14:15]
	v_cvt_pk_bf16_f32 v32, v32, v33
	v_cvt_pk_bf16_f32 v33, v34, v35
	v_cvt_pk_bf16_f32 v34, v24, v25
	v_add_u32_e32 v24, s0, v153
	v_cvt_pk_bf16_f32 v35, v26, v27
	global_store_dwordx4 v48, v[32:35], s[14:15] offset:256
	s_nop 1
	v_lshl_add_u32 v32, v24, 11, v144
	v_cvt_pk_bf16_f32 v24, v36, v37
	v_cvt_pk_bf16_f32 v25, v38, v39
	v_cvt_pk_bf16_f32 v26, v28, v29
	v_cvt_pk_bf16_f32 v27, v30, v31
	global_store_dwordx4 v32, v[24:27], s[14:15]
	v_cvt_pk_bf16_f32 v16, v16, v17
	v_cvt_pk_bf16_f32 v17, v18, v19
	v_cvt_pk_bf16_f32 v18, v8, v9
	v_add_u32_e32 v8, s0, v154
	v_cvt_pk_bf16_f32 v19, v10, v11
	global_store_dwordx4 v32, v[16:19], s[14:15] offset:256
	s_mov_b64 s[0:1], -1
	s_nop 0
	v_lshl_add_u32 v16, v8, 11, v144
	v_cvt_pk_bf16_f32 v8, v20, v21
	v_cvt_pk_bf16_f32 v9, v22, v23
	v_cvt_pk_bf16_f32 v10, v12, v13
	v_cvt_pk_bf16_f32 v11, v14, v15
	global_store_dwordx4 v16, v[8:11], s[14:15]
	v_cvt_pk_bf16_f32 v4, v4, v5
	v_cvt_pk_bf16_f32 v5, v6, v7
	v_cvt_pk_bf16_f32 v6, v0, v1
	v_cvt_pk_bf16_f32 v7, v2, v3
	global_store_dwordx4 v16, v[4:7], s[14:15] offset:256
	s_cbranch_vccnz .LBB0_167
	s_andn2_b64 vcc, exec, s[10:11]
	s_cbranch_vccnz .LBB0_166
	s_barrier
	s_branch .LBB0_166

.LBB0_667:
	s_lshl_b32 s4, s34, 8
	v_add_u32_e32 v146, s4, v129
	v_ashrrev_i32_e32 v147, 31, v146
	v_lshl_or_b32 v162, s33, 8, v157
	v_lshlrev_b64 v[146:147], 11, v[146:147]
	v_ashrrev_i32_e32 v163, 31, v162
	v_lshl_add_u64 v[164:165], s[86:87], 0, v[146:147]
	v_lshlrev_b64 v[146:147], 1, v[162:163]
	v_lshl_add_u64 v[162:163], v[164:165], 0, v[146:147]
	v_cvt_pk_bf16_f32 v124, v124, v125
	v_cvt_pk_bf16_f32 v125, v126, v127
	v_cvt_pk_bf16_f32 v126, v120, v121
	v_cvt_pk_bf16_f32 v127, v122, v123
	global_store_dwordx4 v[162:163], v[124:127], off
	v_cvt_pk_bf16_f32 v112, v112, v113
	v_cvt_pk_bf16_f32 v113, v114, v115
	v_cvt_pk_bf16_f32 v114, v104, v105
	v_add_u32_e32 v104, s4, v150
	v_cvt_pk_bf16_f32 v115, v106, v107
	global_store_dwordx4 v[162:163], v[112:115], off offset:256
	s_andn2_b64 vcc, exec, s[6:7]
	s_nop 0
	v_lshl_add_u32 v112, v104, 11, v146
	v_cvt_pk_bf16_f32 v104, v116, v117
	v_cvt_pk_bf16_f32 v105, v118, v119
	v_cvt_pk_bf16_f32 v106, v108, v109
	v_cvt_pk_bf16_f32 v107, v110, v111
	global_store_dwordx4 v112, v[104:107], s[86:87]
	v_cvt_pk_bf16_f32 v96, v96, v97
	v_cvt_pk_bf16_f32 v97, v98, v99
	v_cvt_pk_bf16_f32 v98, v88, v89
	v_add_u32_e32 v88, s4, v151
	v_cvt_pk_bf16_f32 v99, v90, v91
	global_store_dwordx4 v112, v[96:99], s[86:87] offset:256
	s_nop 1
	v_lshl_add_u32 v96, v88, 11, v146
	v_cvt_pk_bf16_f32 v88, v100, v101
	v_cvt_pk_bf16_f32 v89, v102, v103
	v_cvt_pk_bf16_f32 v90, v92, v93
	v_cvt_pk_bf16_f32 v91, v94, v95
	global_store_dwordx4 v96, v[88:91], s[86:87]
	v_cvt_pk_bf16_f32 v80, v80, v81
	v_cvt_pk_bf16_f32 v81, v82, v83
	v_cvt_pk_bf16_f32 v82, v72, v73
	v_add_u32_e32 v72, s4, v152
	v_cvt_pk_bf16_f32 v83, v74, v75
	global_store_dwordx4 v96, v[80:83], s[86:87] offset:256
	s_nop 1
	v_lshl_add_u32 v80, v72, 11, v146
	v_cvt_pk_bf16_f32 v72, v84, v85
	v_cvt_pk_bf16_f32 v73, v86, v87
	v_cvt_pk_bf16_f32 v74, v76, v77
	v_cvt_pk_bf16_f32 v75, v78, v79
	global_store_dwordx4 v80, v[72:75], s[86:87]
	v_cvt_pk_bf16_f32 v68, v68, v69
	v_cvt_pk_bf16_f32 v69, v70, v71
	v_cvt_pk_bf16_f32 v70, v64, v65
	v_add_u32_e32 v64, s4, v153
	v_lshl_add_u32 v64, v64, 11, v146
	v_cvt_pk_bf16_f32 v71, v66, v67
	global_store_dwordx4 v80, v[68:71], s[86:87] offset:256
	v_cvt_pk_bf16_f32 v60, v60, v61
	v_cvt_pk_bf16_f32 v61, v62, v63
	v_cvt_pk_bf16_f32 v62, v56, v57
	v_cvt_pk_bf16_f32 v63, v58, v59
	global_store_dwordx4 v64, v[60:63], s[86:87]
	v_cvt_pk_bf16_f32 v48, v48, v49
	v_cvt_pk_bf16_f32 v49, v50, v51
	v_cvt_pk_bf16_f32 v50, v40, v41
	v_add_u32_e32 v40, s4, v154
	v_cvt_pk_bf16_f32 v51, v42, v43
	global_store_dwordx4 v64, v[48:51], s[86:87] offset:256
	s_nop 1
	v_lshl_add_u32 v48, v40, 11, v146
	v_cvt_pk_bf16_f32 v40, v52, v53
	v_cvt_pk_bf16_f32 v41, v54, v55
	v_cvt_pk_bf16_f32 v42, v44, v45
	v_cvt_pk_bf16_f32 v43, v46, v47
	global_store_dwordx4 v48, v[40:43], s[86:87]
	v_cvt_pk_bf16_f32 v32, v32, v33
	v_cvt_pk_bf16_f32 v33, v34, v35
	v_cvt_pk_bf16_f32 v34, v24, v25
	v_add_u32_e32 v24, s4, v155
	v_cvt_pk_bf16_f32 v35, v26, v27
	global_store_dwordx4 v48, v[32:35], s[86:87] offset:256
	s_nop 1
	v_lshl_add_u32 v32, v24, 11, v146
	v_cvt_pk_bf16_f32 v24, v36, v37
	v_cvt_pk_bf16_f32 v25, v38, v39
	v_cvt_pk_bf16_f32 v26, v28, v29
	v_cvt_pk_bf16_f32 v27, v30, v31
	global_store_dwordx4 v32, v[24:27], s[86:87]
	v_cvt_pk_bf16_f32 v16, v16, v17
	v_cvt_pk_bf16_f32 v17, v18, v19
	v_cvt_pk_bf16_f32 v18, v8, v9
	v_add_u32_e32 v8, s4, v156
	v_cvt_pk_bf16_f32 v19, v10, v11
	global_store_dwordx4 v32, v[16:19], s[86:87] offset:256
	s_mov_b64 s[4:5], -1
	s_nop 0
	v_lshl_add_u32 v16, v8, 11, v146
	v_cvt_pk_bf16_f32 v8, v20, v21
	v_cvt_pk_bf16_f32 v9, v22, v23
	v_cvt_pk_bf16_f32 v10, v12, v13
	v_cvt_pk_bf16_f32 v11, v14, v15
	global_store_dwordx4 v16, v[8:11], s[86:87]
	v_cvt_pk_bf16_f32 v4, v4, v5
	v_cvt_pk_bf16_f32 v5, v6, v7
	v_cvt_pk_bf16_f32 v6, v0, v1
	v_cvt_pk_bf16_f32 v7, v2, v3
	global_store_dwordx4 v16, v[4:7], s[86:87] offset:256
	s_cbranch_vccnz .LBB0_656
	s_andn2_b64 vcc, exec, s[12:13]
	s_cbranch_vccnz .LBB0_655
	s_barrier
	s_branch .LBB0_655

.LBB0_691:
	s_lshl_b32 s4, s30, 8
	v_add_u32_e32 v142, s4, v129
	v_ashrrev_i32_e32 v143, 31, v142
	v_lshl_or_b32 v158, s33, 8, v153
	v_lshlrev_b64 v[142:143], 11, v[142:143]
	v_ashrrev_i32_e32 v159, 31, v158
	v_lshl_add_u64 v[160:161], s[16:17], 0, v[142:143]
	v_lshlrev_b64 v[142:143], 1, v[158:159]
	v_lshl_add_u64 v[158:159], v[160:161], 0, v[142:143]
	v_cvt_pk_bf16_f32 v124, v124, v125
	v_cvt_pk_bf16_f32 v125, v126, v127
	v_cvt_pk_bf16_f32 v126, v120, v121
	v_cvt_pk_bf16_f32 v127, v122, v123
	global_store_dwordx4 v[158:159], v[124:127], off
	v_cvt_pk_bf16_f32 v112, v112, v113
	v_cvt_pk_bf16_f32 v113, v114, v115
	v_cvt_pk_bf16_f32 v114, v104, v105
	v_add_u32_e32 v104, s4, v145
	v_cvt_pk_bf16_f32 v115, v106, v107
	global_store_dwordx4 v[158:159], v[112:115], off offset:256
	s_andn2_b64 vcc, exec, s[6:7]
	s_nop 0
	v_lshl_add_u32 v112, v104, 11, v142
	v_cvt_pk_bf16_f32 v104, v116, v117
	v_cvt_pk_bf16_f32 v105, v118, v119
	v_cvt_pk_bf16_f32 v106, v108, v109
	v_cvt_pk_bf16_f32 v107, v110, v111
	global_store_dwordx4 v112, v[104:107], s[16:17]
	v_cvt_pk_bf16_f32 v96, v96, v97
	v_cvt_pk_bf16_f32 v97, v98, v99
	v_cvt_pk_bf16_f32 v98, v88, v89
	v_add_u32_e32 v88, s4, v146
	v_cvt_pk_bf16_f32 v99, v90, v91
	global_store_dwordx4 v112, v[96:99], s[16:17] offset:256
	s_nop 1
	v_lshl_add_u32 v96, v88, 11, v142
	v_cvt_pk_bf16_f32 v88, v100, v101
	v_cvt_pk_bf16_f32 v89, v102, v103
	v_cvt_pk_bf16_f32 v90, v92, v93
	v_cvt_pk_bf16_f32 v91, v94, v95
	global_store_dwordx4 v96, v[88:91], s[16:17]
	v_cvt_pk_bf16_f32 v80, v80, v81
	v_cvt_pk_bf16_f32 v81, v82, v83
	v_cvt_pk_bf16_f32 v82, v72, v73
	v_add_u32_e32 v72, s4, v147
	v_cvt_pk_bf16_f32 v83, v74, v75
	global_store_dwordx4 v96, v[80:83], s[16:17] offset:256
	s_nop 1
	v_lshl_add_u32 v80, v72, 11, v142
	v_cvt_pk_bf16_f32 v72, v84, v85
	v_cvt_pk_bf16_f32 v73, v86, v87
	v_cvt_pk_bf16_f32 v74, v76, v77
	v_cvt_pk_bf16_f32 v75, v78, v79
	global_store_dwordx4 v80, v[72:75], s[16:17]
	v_cvt_pk_bf16_f32 v68, v68, v69
	v_cvt_pk_bf16_f32 v69, v70, v71
	v_cvt_pk_bf16_f32 v70, v64, v65
	v_add_u32_e32 v64, s4, v149
	v_lshl_add_u32 v64, v64, 11, v142
	v_cvt_pk_bf16_f32 v71, v66, v67
	global_store_dwordx4 v80, v[68:71], s[16:17] offset:256
	v_cvt_pk_bf16_f32 v60, v60, v61
	v_cvt_pk_bf16_f32 v61, v62, v63
	v_cvt_pk_bf16_f32 v62, v56, v57
	v_cvt_pk_bf16_f32 v63, v58, v59
	global_store_dwordx4 v64, v[60:63], s[16:17]
	v_cvt_pk_bf16_f32 v48, v48, v49
	v_cvt_pk_bf16_f32 v49, v50, v51
	v_cvt_pk_bf16_f32 v50, v40, v41
	v_add_u32_e32 v40, s4, v150
	v_cvt_pk_bf16_f32 v51, v42, v43
	global_store_dwordx4 v64, v[48:51], s[16:17] offset:256
	s_nop 1
	v_lshl_add_u32 v48, v40, 11, v142
	v_cvt_pk_bf16_f32 v40, v52, v53
	v_cvt_pk_bf16_f32 v41, v54, v55
	v_cvt_pk_bf16_f32 v42, v44, v45
	v_cvt_pk_bf16_f32 v43, v46, v47
	global_store_dwordx4 v48, v[40:43], s[16:17]
	v_cvt_pk_bf16_f32 v32, v32, v33
	v_cvt_pk_bf16_f32 v33, v34, v35
	v_cvt_pk_bf16_f32 v34, v24, v25
	v_add_u32_e32 v24, s4, v151
	v_cvt_pk_bf16_f32 v35, v26, v27
	global_store_dwordx4 v48, v[32:35], s[16:17] offset:256
	s_nop 1
	v_lshl_add_u32 v32, v24, 11, v142
	v_cvt_pk_bf16_f32 v24, v36, v37
	v_cvt_pk_bf16_f32 v25, v38, v39
	v_cvt_pk_bf16_f32 v26, v28, v29
	v_cvt_pk_bf16_f32 v27, v30, v31
	global_store_dwordx4 v32, v[24:27], s[16:17]
	v_cvt_pk_bf16_f32 v16, v16, v17
	v_cvt_pk_bf16_f32 v17, v18, v19
	v_cvt_pk_bf16_f32 v18, v8, v9
	v_add_u32_e32 v8, s4, v152
	v_cvt_pk_bf16_f32 v19, v10, v11
	global_store_dwordx4 v32, v[16:19], s[16:17] offset:256
	s_mov_b64 s[4:5], -1
	s_nop 0
	v_lshl_add_u32 v16, v8, 11, v142
	v_cvt_pk_bf16_f32 v8, v20, v21
	v_cvt_pk_bf16_f32 v9, v22, v23
	v_cvt_pk_bf16_f32 v10, v12, v13
	v_cvt_pk_bf16_f32 v11, v14, v15
	global_store_dwordx4 v16, v[8:11], s[16:17]
	v_cvt_pk_bf16_f32 v4, v4, v5
	v_cvt_pk_bf16_f32 v5, v6, v7
	v_cvt_pk_bf16_f32 v6, v0, v1
	v_cvt_pk_bf16_f32 v7, v2, v3
	global_store_dwordx4 v16, v[4:7], s[16:17] offset:256
	s_cbranch_vccnz .LBB0_680
	s_andn2_b64 vcc, exec, s[10:11]
	s_cbranch_vccnz .LBB0_679
	s_barrier
	s_branch .LBB0_679

.LBB0_973:
	s_lshl_b32 s4, s20, 8
	v_add_u32_e32 v144, s4, v146
	v_ashrrev_i32_e32 v145, 31, v144
	v_lshl_or_b32 v160, s40, 8, v155
	v_lshlrev_b64 v[144:145], 11, v[144:145]
	v_ashrrev_i32_e32 v161, 31, v160
	v_lshl_add_u64 v[162:163], s[82:83], 0, v[144:145]
	v_lshlrev_b64 v[144:145], 1, v[160:161]
	v_lshl_add_u64 v[160:161], v[162:163], 0, v[144:145]
	v_cvt_pk_bf16_f32 v124, v124, v125
	v_cvt_pk_bf16_f32 v125, v126, v127
	v_cvt_pk_bf16_f32 v126, v120, v121
	v_cvt_pk_bf16_f32 v127, v122, v123
	global_store_dwordx4 v[160:161], v[124:127], off
	v_cvt_pk_bf16_f32 v112, v112, v113
	v_cvt_pk_bf16_f32 v113, v114, v115
	v_cvt_pk_bf16_f32 v114, v104, v105
	v_add_u32_e32 v104, s4, v148
	v_cvt_pk_bf16_f32 v115, v106, v107
	global_store_dwordx4 v[160:161], v[112:115], off offset:256
	s_andn2_b64 vcc, exec, s[6:7]
	s_nop 0
	v_lshl_add_u32 v112, v104, 11, v144
	v_cvt_pk_bf16_f32 v104, v116, v117
	v_cvt_pk_bf16_f32 v105, v118, v119
	v_cvt_pk_bf16_f32 v106, v108, v109
	v_cvt_pk_bf16_f32 v107, v110, v111
	global_store_dwordx4 v112, v[104:107], s[82:83]
	v_cvt_pk_bf16_f32 v96, v96, v97
	v_cvt_pk_bf16_f32 v97, v98, v99
	v_cvt_pk_bf16_f32 v98, v88, v89
	v_add_u32_e32 v88, s4, v149
	v_cvt_pk_bf16_f32 v99, v90, v91
	global_store_dwordx4 v112, v[96:99], s[82:83] offset:256
	s_nop 1
	v_lshl_add_u32 v96, v88, 11, v144
	v_cvt_pk_bf16_f32 v88, v100, v101
	v_cvt_pk_bf16_f32 v89, v102, v103
	v_cvt_pk_bf16_f32 v90, v92, v93
	v_cvt_pk_bf16_f32 v91, v94, v95
	global_store_dwordx4 v96, v[88:91], s[82:83]
	v_cvt_pk_bf16_f32 v80, v80, v81
	v_cvt_pk_bf16_f32 v81, v82, v83
	v_cvt_pk_bf16_f32 v82, v72, v73
	v_add_u32_e32 v72, s4, v150
	v_cvt_pk_bf16_f32 v83, v74, v75
	global_store_dwordx4 v96, v[80:83], s[82:83] offset:256
	s_nop 1
	v_lshl_add_u32 v80, v72, 11, v144
	v_cvt_pk_bf16_f32 v72, v84, v85
	v_cvt_pk_bf16_f32 v73, v86, v87
	v_cvt_pk_bf16_f32 v74, v76, v77
	v_cvt_pk_bf16_f32 v75, v78, v79
	global_store_dwordx4 v80, v[72:75], s[82:83]
	v_cvt_pk_bf16_f32 v68, v68, v69
	v_cvt_pk_bf16_f32 v69, v70, v71
	v_cvt_pk_bf16_f32 v70, v64, v65
	v_add_u32_e32 v64, s4, v151
	v_lshl_add_u32 v64, v64, 11, v144
	v_cvt_pk_bf16_f32 v71, v66, v67
	global_store_dwordx4 v80, v[68:71], s[82:83] offset:256
	v_cvt_pk_bf16_f32 v60, v60, v61
	v_cvt_pk_bf16_f32 v61, v62, v63
	v_cvt_pk_bf16_f32 v62, v56, v57
	v_cvt_pk_bf16_f32 v63, v58, v59
	global_store_dwordx4 v64, v[60:63], s[82:83]
	v_cvt_pk_bf16_f32 v48, v48, v49
	v_cvt_pk_bf16_f32 v49, v50, v51
	v_cvt_pk_bf16_f32 v50, v40, v41
	v_add_u32_e32 v40, s4, v152
	v_cvt_pk_bf16_f32 v51, v42, v43
	global_store_dwordx4 v64, v[48:51], s[82:83] offset:256
	s_nop 1
	v_lshl_add_u32 v48, v40, 11, v144
	v_cvt_pk_bf16_f32 v40, v52, v53
	v_cvt_pk_bf16_f32 v41, v54, v55
	v_cvt_pk_bf16_f32 v42, v44, v45
	v_cvt_pk_bf16_f32 v43, v46, v47
	global_store_dwordx4 v48, v[40:43], s[82:83]
	v_cvt_pk_bf16_f32 v32, v32, v33
	v_cvt_pk_bf16_f32 v33, v34, v35
	v_cvt_pk_bf16_f32 v34, v24, v25
	v_add_u32_e32 v24, s4, v153
	v_cvt_pk_bf16_f32 v35, v26, v27
	global_store_dwordx4 v48, v[32:35], s[82:83] offset:256
	s_nop 1
	v_lshl_add_u32 v32, v24, 11, v144
	v_cvt_pk_bf16_f32 v24, v36, v37
	v_cvt_pk_bf16_f32 v25, v38, v39
	v_cvt_pk_bf16_f32 v26, v28, v29
	v_cvt_pk_bf16_f32 v27, v30, v31
	global_store_dwordx4 v32, v[24:27], s[82:83]
	v_cvt_pk_bf16_f32 v16, v16, v17
	v_cvt_pk_bf16_f32 v17, v18, v19
	v_cvt_pk_bf16_f32 v18, v8, v9
	v_add_u32_e32 v8, s4, v154
	v_cvt_pk_bf16_f32 v19, v10, v11
	global_store_dwordx4 v32, v[16:19], s[82:83] offset:256
	s_mov_b64 s[4:5], -1
	s_nop 0
	v_lshl_add_u32 v16, v8, 11, v144
	v_cvt_pk_bf16_f32 v8, v20, v21
	v_cvt_pk_bf16_f32 v9, v22, v23
	v_cvt_pk_bf16_f32 v10, v12, v13
	v_cvt_pk_bf16_f32 v11, v14, v15
	global_store_dwordx4 v16, v[8:11], s[82:83]
	v_cvt_pk_bf16_f32 v4, v4, v5
	v_cvt_pk_bf16_f32 v5, v6, v7
	v_cvt_pk_bf16_f32 v6, v0, v1
	v_cvt_pk_bf16_f32 v7, v2, v3
	global_store_dwordx4 v16, v[4:7], s[82:83] offset:256
	s_cbranch_vccnz .LBB0_962
	s_andn2_b64 vcc, exec, s[0:1]
	s_cbranch_vccnz .LBB0_961
	s_barrier
	s_branch .LBB0_961

.LBB0_1556:
	s_lshl_b32 s4, s20, 8
	v_add_u32_e32 v144, s4, v146
	v_ashrrev_i32_e32 v145, 31, v144
	v_lshl_or_b32 v160, s40, 8, v155
	v_lshlrev_b64 v[144:145], 11, v[144:145]
	v_ashrrev_i32_e32 v161, 31, v160
	v_lshl_add_u64 v[162:163], s[86:87], 0, v[144:145]
	v_lshlrev_b64 v[144:145], 1, v[160:161]
	v_lshl_add_u64 v[160:161], v[162:163], 0, v[144:145]
	v_cvt_pk_bf16_f32 v124, v124, v125
	v_cvt_pk_bf16_f32 v125, v126, v127
	v_cvt_pk_bf16_f32 v126, v120, v121
	v_cvt_pk_bf16_f32 v127, v122, v123
	global_store_dwordx4 v[160:161], v[124:127], off
	v_cvt_pk_bf16_f32 v112, v112, v113
	v_cvt_pk_bf16_f32 v113, v114, v115
	v_cvt_pk_bf16_f32 v114, v104, v105
	v_add_u32_e32 v104, s4, v148
	v_cvt_pk_bf16_f32 v115, v106, v107
	global_store_dwordx4 v[160:161], v[112:115], off offset:256
	s_andn2_b64 vcc, exec, s[6:7]
	s_nop 0
	v_lshl_add_u32 v112, v104, 11, v144
	v_cvt_pk_bf16_f32 v104, v116, v117
	v_cvt_pk_bf16_f32 v105, v118, v119
	v_cvt_pk_bf16_f32 v106, v108, v109
	v_cvt_pk_bf16_f32 v107, v110, v111
	global_store_dwordx4 v112, v[104:107], s[86:87]
	v_cvt_pk_bf16_f32 v96, v96, v97
	v_cvt_pk_bf16_f32 v97, v98, v99
	v_cvt_pk_bf16_f32 v98, v88, v89
	v_add_u32_e32 v88, s4, v149
	v_cvt_pk_bf16_f32 v99, v90, v91
	global_store_dwordx4 v112, v[96:99], s[86:87] offset:256
	s_nop 1
	v_lshl_add_u32 v96, v88, 11, v144
	v_cvt_pk_bf16_f32 v88, v100, v101
	v_cvt_pk_bf16_f32 v89, v102, v103
	v_cvt_pk_bf16_f32 v90, v92, v93
	v_cvt_pk_bf16_f32 v91, v94, v95
	global_store_dwordx4 v96, v[88:91], s[86:87]
	v_cvt_pk_bf16_f32 v80, v80, v81
	v_cvt_pk_bf16_f32 v81, v82, v83
	v_cvt_pk_bf16_f32 v82, v72, v73
	v_add_u32_e32 v72, s4, v150
	v_cvt_pk_bf16_f32 v83, v74, v75
	global_store_dwordx4 v96, v[80:83], s[86:87] offset:256
	s_nop 1
	v_lshl_add_u32 v80, v72, 11, v144
	v_cvt_pk_bf16_f32 v72, v84, v85
	v_cvt_pk_bf16_f32 v73, v86, v87
	v_cvt_pk_bf16_f32 v74, v76, v77
	v_cvt_pk_bf16_f32 v75, v78, v79
	global_store_dwordx4 v80, v[72:75], s[86:87]
	v_cvt_pk_bf16_f32 v68, v68, v69
	v_cvt_pk_bf16_f32 v69, v70, v71
	v_cvt_pk_bf16_f32 v70, v64, v65
	v_add_u32_e32 v64, s4, v151
	v_lshl_add_u32 v64, v64, 11, v144
	v_cvt_pk_bf16_f32 v71, v66, v67
	global_store_dwordx4 v80, v[68:71], s[86:87] offset:256
	v_cvt_pk_bf16_f32 v60, v60, v61
	v_cvt_pk_bf16_f32 v61, v62, v63
	v_cvt_pk_bf16_f32 v62, v56, v57
	v_cvt_pk_bf16_f32 v63, v58, v59
	global_store_dwordx4 v64, v[60:63], s[86:87]
	v_cvt_pk_bf16_f32 v48, v48, v49
	v_cvt_pk_bf16_f32 v49, v50, v51
	v_cvt_pk_bf16_f32 v50, v40, v41
	v_add_u32_e32 v40, s4, v152
	v_cvt_pk_bf16_f32 v51, v42, v43
	global_store_dwordx4 v64, v[48:51], s[86:87] offset:256
	s_nop 1
	v_lshl_add_u32 v48, v40, 11, v144
	v_cvt_pk_bf16_f32 v40, v52, v53
	v_cvt_pk_bf16_f32 v41, v54, v55
	v_cvt_pk_bf16_f32 v42, v44, v45
	v_cvt_pk_bf16_f32 v43, v46, v47
	global_store_dwordx4 v48, v[40:43], s[86:87]
	v_cvt_pk_bf16_f32 v32, v32, v33
	v_cvt_pk_bf16_f32 v33, v34, v35
	v_cvt_pk_bf16_f32 v34, v24, v25
	v_add_u32_e32 v24, s4, v153
	v_cvt_pk_bf16_f32 v35, v26, v27
	global_store_dwordx4 v48, v[32:35], s[86:87] offset:256
	s_nop 1
	v_lshl_add_u32 v32, v24, 11, v144
	v_cvt_pk_bf16_f32 v24, v36, v37
	v_cvt_pk_bf16_f32 v25, v38, v39
	v_cvt_pk_bf16_f32 v26, v28, v29
	v_cvt_pk_bf16_f32 v27, v30, v31
	global_store_dwordx4 v32, v[24:27], s[86:87]
	v_cvt_pk_bf16_f32 v16, v16, v17
	v_cvt_pk_bf16_f32 v17, v18, v19
	v_cvt_pk_bf16_f32 v18, v8, v9
	v_add_u32_e32 v8, s4, v154
	v_cvt_pk_bf16_f32 v19, v10, v11
	global_store_dwordx4 v32, v[16:19], s[86:87] offset:256
	s_mov_b64 s[4:5], -1
	s_nop 0
	v_lshl_add_u32 v16, v8, 11, v144
	v_cvt_pk_bf16_f32 v8, v20, v21
	v_cvt_pk_bf16_f32 v9, v22, v23
	v_cvt_pk_bf16_f32 v10, v12, v13
	v_cvt_pk_bf16_f32 v11, v14, v15
	global_store_dwordx4 v16, v[8:11], s[86:87]
	v_cvt_pk_bf16_f32 v4, v4, v5
	v_cvt_pk_bf16_f32 v5, v6, v7
	v_cvt_pk_bf16_f32 v6, v0, v1
	v_cvt_pk_bf16_f32 v7, v2, v3
	global_store_dwordx4 v16, v[4:7], s[86:87] offset:256
	s_cbranch_vccnz .LBB0_1545
	s_andn2_b64 vcc, exec, s[0:1]
	s_cbranch_vccnz .LBB0_1544
	s_barrier
	s_branch .LBB0_1544

.LBB0_1683:
	s_lshl_b32 s4, s20, 8
	v_add_u32_e32 v140, s4, v142
	v_ashrrev_i32_e32 v141, 31, v140
	v_lshl_or_b32 v156, s62, 8, v151
	v_lshlrev_b64 v[140:141], 11, v[140:141]
	v_ashrrev_i32_e32 v157, 31, v156
	v_lshl_add_u64 v[158:159], s[80:81], 0, v[140:141]
	v_lshlrev_b64 v[140:141], 1, v[156:157]
	v_lshl_add_u64 v[156:157], v[158:159], 0, v[140:141]
	v_cvt_pk_bf16_f32 v124, v124, v125
	v_cvt_pk_bf16_f32 v125, v126, v127
	v_cvt_pk_bf16_f32 v126, v120, v121
	v_cvt_pk_bf16_f32 v127, v122, v123
	global_store_dwordx4 v[156:157], v[124:127], off
	v_cvt_pk_bf16_f32 v112, v112, v113
	v_cvt_pk_bf16_f32 v113, v114, v115
	v_cvt_pk_bf16_f32 v114, v104, v105
	v_add_u32_e32 v104, s4, v144
	v_cvt_pk_bf16_f32 v115, v106, v107
	global_store_dwordx4 v[156:157], v[112:115], off offset:256
	s_andn2_b64 vcc, exec, s[6:7]
	s_nop 0
	v_lshl_add_u32 v112, v104, 11, v140
	v_cvt_pk_bf16_f32 v104, v116, v117
	v_cvt_pk_bf16_f32 v105, v118, v119
	v_cvt_pk_bf16_f32 v106, v108, v109
	v_cvt_pk_bf16_f32 v107, v110, v111
	global_store_dwordx4 v112, v[104:107], s[80:81]
	v_cvt_pk_bf16_f32 v96, v96, v97
	v_cvt_pk_bf16_f32 v97, v98, v99
	v_cvt_pk_bf16_f32 v98, v88, v89
	v_add_u32_e32 v88, s4, v145
	v_cvt_pk_bf16_f32 v99, v90, v91
	global_store_dwordx4 v112, v[96:99], s[80:81] offset:256
	s_nop 1
	v_lshl_add_u32 v96, v88, 11, v140
	v_cvt_pk_bf16_f32 v88, v100, v101
	v_cvt_pk_bf16_f32 v89, v102, v103
	v_cvt_pk_bf16_f32 v90, v92, v93
	v_cvt_pk_bf16_f32 v91, v94, v95
	global_store_dwordx4 v96, v[88:91], s[80:81]
	v_cvt_pk_bf16_f32 v80, v80, v81
	v_cvt_pk_bf16_f32 v81, v82, v83
	v_cvt_pk_bf16_f32 v82, v72, v73
	v_add_u32_e32 v72, s4, v146
	v_cvt_pk_bf16_f32 v83, v74, v75
	global_store_dwordx4 v96, v[80:83], s[80:81] offset:256
	s_nop 1
	v_lshl_add_u32 v80, v72, 11, v140
	v_cvt_pk_bf16_f32 v72, v84, v85
	v_cvt_pk_bf16_f32 v73, v86, v87
	v_cvt_pk_bf16_f32 v74, v76, v77
	v_cvt_pk_bf16_f32 v75, v78, v79
	global_store_dwordx4 v80, v[72:75], s[80:81]
	v_cvt_pk_bf16_f32 v68, v68, v69
	v_cvt_pk_bf16_f32 v69, v70, v71
	v_cvt_pk_bf16_f32 v70, v64, v65
	v_add_u32_e32 v64, s4, v147
	v_lshl_add_u32 v64, v64, 11, v140
	v_cvt_pk_bf16_f32 v71, v66, v67
	global_store_dwordx4 v80, v[68:71], s[80:81] offset:256
	v_cvt_pk_bf16_f32 v60, v60, v61
	v_cvt_pk_bf16_f32 v61, v62, v63
	v_cvt_pk_bf16_f32 v62, v56, v57
	v_cvt_pk_bf16_f32 v63, v58, v59
	global_store_dwordx4 v64, v[60:63], s[80:81]
	v_cvt_pk_bf16_f32 v48, v48, v49
	v_cvt_pk_bf16_f32 v49, v50, v51
	v_cvt_pk_bf16_f32 v50, v40, v41
	v_add_u32_e32 v40, s4, v148
	v_cvt_pk_bf16_f32 v51, v42, v43
	global_store_dwordx4 v64, v[48:51], s[80:81] offset:256
	s_nop 1
	v_lshl_add_u32 v48, v40, 11, v140
	v_cvt_pk_bf16_f32 v40, v52, v53
	v_cvt_pk_bf16_f32 v41, v54, v55
	v_cvt_pk_bf16_f32 v42, v44, v45
	v_cvt_pk_bf16_f32 v43, v46, v47
	global_store_dwordx4 v48, v[40:43], s[80:81]
	v_cvt_pk_bf16_f32 v32, v32, v33
	v_cvt_pk_bf16_f32 v33, v34, v35
	v_cvt_pk_bf16_f32 v34, v24, v25
	v_add_u32_e32 v24, s4, v149
	v_cvt_pk_bf16_f32 v35, v26, v27
	global_store_dwordx4 v48, v[32:35], s[80:81] offset:256
	s_nop 1
	v_lshl_add_u32 v32, v24, 11, v140
	v_cvt_pk_bf16_f32 v24, v36, v37
	v_cvt_pk_bf16_f32 v25, v38, v39
	v_cvt_pk_bf16_f32 v26, v28, v29
	v_cvt_pk_bf16_f32 v27, v30, v31
	global_store_dwordx4 v32, v[24:27], s[80:81]
	v_cvt_pk_bf16_f32 v16, v16, v17
	v_cvt_pk_bf16_f32 v17, v18, v19
	v_cvt_pk_bf16_f32 v18, v8, v9
	v_add_u32_e32 v8, s4, v150
	v_cvt_pk_bf16_f32 v19, v10, v11
	global_store_dwordx4 v32, v[16:19], s[80:81] offset:256
	s_mov_b64 s[4:5], -1
	s_nop 0
	v_lshl_add_u32 v16, v8, 11, v140
	v_cvt_pk_bf16_f32 v8, v20, v21
	v_cvt_pk_bf16_f32 v9, v22, v23
	v_cvt_pk_bf16_f32 v10, v12, v13
	v_cvt_pk_bf16_f32 v11, v14, v15
	global_store_dwordx4 v16, v[8:11], s[80:81]
	v_cvt_pk_bf16_f32 v4, v4, v5
	v_cvt_pk_bf16_f32 v5, v6, v7
	v_cvt_pk_bf16_f32 v6, v0, v1
	v_cvt_pk_bf16_f32 v7, v2, v3
	global_store_dwordx4 v16, v[4:7], s[80:81] offset:256
	s_cbranch_vccnz .LBB0_1672
	s_andn2_b64 vcc, exec, s[0:1]
	s_cbranch_vccnz .LBB0_1671
	s_barrier
	s_branch .LBB0_1671
